# layer-0 norm rows rebalanced onto the 192 workgroups without a memory-KV GEMM tile (overlaps that GEMM)
# speedup vs baseline: 1.0014x; 1.0014x over previous
.LBB0_149:
	s_or_b64 exec, exec, s[6:7]
	s_waitcnt vmcnt(0)
	v_ashrrev_i32_e32 v2, 6, v4
	v_readlane_b32 s0, v253, 2
	s_waitcnt lgkmcnt(0)
	s_barrier
	v_add_u32_e32 v180, s0, v2
	s_mov_b32 s48, s75
	s_cmp_lg_u32 s83, 0
	s_cbranch_scc1 .Lp1_bal_done
	s_movk_i32 s48, 0x600
	v_subrev_u32_e32 v180, 0x200, v180
	s_cmpk_ge_u32 s64, 0x40
	s_cbranch_scc1 .Lp1_bal_done
	v_mov_b32_e32 v180, s2
.Lp1_bal_done:
	v_cmp_gt_i32_e32 vcc, s2, v180
	s_and_saveexec_b64 s[10:11], vcc
	s_cbranch_execz .LBB0_156
	v_ashrrev_i32_e32 v181, 31, v180
	v_and_b32_e32 v134, 63, v4
	v_lshlrev_b64 v[2:3], 12, v[180:181]
	v_lshl_add_u64 v[2:3], v[212:213], 0, v[2:3]
	v_lshlrev_b32_e32 v166, 4, v134
	v_lshl_add_u64 v[2:3], v[2:3], 0, v[166:167]
	global_load_dwordx4 v[160:163], v[2:3], off
	global_load_dwordx4 v[156:159], v[2:3], off offset:1024
	global_load_dwordx4 v[152:155], v[2:3], off offset:2048
	global_load_dwordx4 v[148:151], v[2:3], off offset:3072
	s_mov_b64 s[6:7], 0x7300000
	s_lshl_b32 s96, s83, 10
	v_lshl_add_u64 v[164:165], v[132:133], 0, s[6:7]
	s_lshl_b64 s[6:7], s[96:97], 2
	v_lshl_add_u64 v[0:1], v[0:1], 0, s[6:7]
	v_lshl_add_u32 v128, v134, 7, 0
	v_lshl_add_u64 v[178:179], v[0:1], 0, v[166:167]
	ds_read_b128 v[0:3], v128
	ds_read_b128 v[4:7], v128 offset:16
	ds_read_b128 v[8:11], v128 offset:32
	ds_read_b128 v[12:15], v128 offset:48
	ds_read_b128 v[16:19], v128 offset:64
	ds_read_b128 v[20:23], v128 offset:80
	ds_read_b128 v[24:27], v128 offset:96
	ds_read_b128 v[28:31], v128 offset:112
	ds_read_b128 v[32:35], v128 offset:8192
	ds_read_b128 v[36:39], v128 offset:8208
	ds_read_b128 v[40:43], v128 offset:8224
	ds_read_b128 v[44:47], v128 offset:8240
	ds_read_b128 v[48:51], v128 offset:8256
	ds_read_b128 v[52:55], v128 offset:8272
	ds_read_b128 v[56:59], v128 offset:8288
	ds_read_b128 v[60:63], v128 offset:8304
	ds_read_b128 v[64:67], v128 offset:16384
	ds_read_b128 v[68:71], v128 offset:16400
	ds_read_b128 v[72:75], v128 offset:16416
	ds_read_b128 v[76:79], v128 offset:16432
	ds_read_b128 v[84:87], v128 offset:16448
	ds_read_b128 v[88:91], v128 offset:16464
	ds_read_b128 v[92:95], v128 offset:16480
	ds_read_b128 v[96:99], v128 offset:16496
	ds_read_b128 v[100:103], v128 offset:24576
	ds_read_b128 v[104:107], v128 offset:24592
	ds_read_b128 v[108:111], v128 offset:24608
	ds_read_b128 v[112:115], v128 offset:24624
	ds_read_b128 v[116:119], v128 offset:24640
	ds_read_b128 v[120:123], v128 offset:24656
	ds_read_b128 v[124:127], v128 offset:24672
	ds_read_b128 v[128:131], v128 offset:24688
	v_lshl_add_u64 v[176:177], v[212:213], 0, v[166:167]
	v_lshlrev_b32_e32 v166, 3, v134
	v_lshl_add_u64 v[132:133], v[132:133], 0, v[166:167]
	s_mov_b64 s[6:7], 0x5300000
	v_cmp_eq_u32_e32 vcc, 0, v134
	v_lshl_add_u64 v[182:183], v[132:133], 0, s[6:7]
	s_mov_b64 s[12:13], 0
	global_load_dwordx4 v[196:199], v[178:179], off
	global_load_dwordx4 v[200:203], v[178:179], off offset:1024
	global_load_dwordx4 v[204:207], v[178:179], off offset:2048
	global_load_dwordx4 v[224:227], v[178:179], off offset:3072
	s_waitcnt vmcnt(0)
	s_branch .LBB0_152

.LBB0_152:
	v_add_u32_e32 v184, s48, v180
	s_movk_i32 s5, 0x3fff
	v_cmp_gt_i32_e64 s[8:9], s2, v184
	v_cmp_lt_i32_e64 s[6:7], s5, v184
	v_mov_b32_e32 v132, v160
	v_mov_b32_e32 v133, v161
	v_mov_b32_e32 v134, v162
	v_mov_b32_e32 v135, v163
	v_mov_b32_e32 v136, v156
	v_mov_b32_e32 v137, v157
	v_mov_b32_e32 v138, v158
	v_mov_b32_e32 v139, v159
	v_mov_b32_e32 v140, v152
	v_mov_b32_e32 v141, v153
	v_mov_b32_e32 v142, v154
	v_mov_b32_e32 v143, v155
	v_mov_b32_e32 v144, v148
	v_mov_b32_e32 v145, v149
	v_mov_b32_e32 v146, v150
	v_mov_b32_e32 v147, v151
	s_and_saveexec_b64 s[14:15], s[8:9]
	s_cbranch_execz .LBB0_154
	v_ashrrev_i32_e32 v185, 31, v184
	v_lshlrev_b64 v[132:133], 12, v[184:185]
	v_lshl_add_u64 v[144:145], v[176:177], 0, v[132:133]
	global_load_dwordx4 v[132:135], v[144:145], off
	global_load_dwordx4 v[136:139], v[144:145], off offset:1024
	global_load_dwordx4 v[140:143], v[144:145], off offset:2048
	s_nop 0
	global_load_dwordx4 v[144:147], v[144:145], off offset:3072
